# v100 with P0 stores at system scope (sc0 sc1) instead of sc1
# baseline (speedup 1.0000x reference)
; #define LAS __attribute__((address_space(3)))
; __device__ __forceinline__ unsigned pk_bf16(float lo, float hi) { typedef __bf16 b2 __attribute__((ext_vector_type(2))); f32x2 v = {lo, hi}; b2 b = __builtin_convertvector(v, b2); return __builtin_bit_cast(unsigned, b); }
; template <bool MAP> __device__ __forceinline__ void p0_transpose_item(const float* W, int K, int N, u16* WT, LAS float* scr, int item, int lane) {
;     ...
;     for (int j = 0; j < 4; ++j) { const int n = (lane >> 3) + 8 * j; const LAS float* s = scr + (8 * c) * 33 + n;
;         u32x4 o; o.x = pk_bf16(s[0 * 33], s[1 * 33]); o.y = pk_bf16(s[2 * 33], s[3 * 33]); o.z = pk_bf16(s[4 * 33], s[5 * 33]); o.w = pk_bf16(s[6 * 33], s[7 * 33]);
;         const int r = MAP ? wt_row_of_col(n0 + n) : (n0 + n);
;         *(u32x4*)(WT + (size_t)r * K + k0 + 8 * c) = o; }
;     asm volatile("s_waitcnt lgkmcnt(0)" ::: "memory");
; }
.LBB0_22:
	s_or_b64 exec, exec, s[10:11]
	v_ashrrev_i32_e32 v23, 31, v22
	s_waitcnt lgkmcnt(3)
	v_cvt_pk_bf16_f32 v14, v14, v15
	s_waitcnt lgkmcnt(2)
	v_cvt_pk_bf16_f32 v15, v16, v17
	s_waitcnt lgkmcnt(1)
	v_cvt_pk_bf16_f32 v16, v18, v19
	v_lshlrev_b64 v[18:19], 11, v[22:23]
	s_waitcnt lgkmcnt(0)
	v_cvt_pk_bf16_f32 v17, v20, v21
	v_lshl_add_u64 v[12:13], v[12:13], 0, v[18:19]
	global_store_dwordx4 v[12:13], v[14:17], off sc0 sc1
	s_waitcnt lgkmcnt(0)

; #define LAS __attribute__((address_space(3)))
; __device__ __forceinline__ unsigned pk_bf16(float lo, float hi) { typedef __bf16 b2 __attribute__((ext_vector_type(2))); f32x2 v = {lo, hi}; b2 b = __builtin_convertvector(v, b2); return __builtin_bit_cast(unsigned, b); }
; template <bool MAP> __device__ __forceinline__ void p0_transpose_item(const float* W, int K, int N, u16* WT, LAS float* scr, int item, int lane) {
;     const int nblk = N / 32, kb = item / nblk, nb = item % nblk, k0 = 64 * kb, n0 = 32 * nb;
;     float tv[32];
; #pragma unroll
;     for (int i = 0; i < 32; ++i) tv[i] = W[(size_t)(k0 + 2 * i + (lane >> 5)) * N + n0 + (lane & 31)];
; #pragma unroll
;     for (int i = 0; i < 32; ++i) scr[(2 * i + (lane >> 5)) * 33 + (lane & 31)] = tv[i];
;     asm volatile("s_waitcnt lgkmcnt(0)" ::: "memory");
;     const int c = lane & 7;
; #pragma unroll
;     for (int j = 0; j < 4; ++j) { const int n = (lane >> 3) + 8 * j; const LAS float* s = scr + (8 * c) * 33 + n;
;         u32x4 o; o.x = pk_bf16(s[0 * 33], s[1 * 33]); o.y = pk_bf16(s[2 * 33], s[3 * 33]); o.z = pk_bf16(s[4 * 33], s[5 * 33]); o.w = pk_bf16(s[6 * 33], s[7 * 33]);
; __device__ __forceinline__ void p0_prologue(const Ptrs& P, LAS unsigned char* lds, int vcu, int G) {
;     ...
;     for (int it = gw; it < NITEMS; it += NGW) {
;         int r = it;
;         if (r < I_IN) { p0_transpose_item<true>(P.w_in, 1024, NIN, (u16*)(P.ws + WS_WT), scr, r, lane); continue; } r -= I_IN;
;         if (r < I_A) { p0_transpose_item<false>(P.wa, 1024, 1024, (u16*)(P.ws + WS_WA), scr, r, lane); continue; } r -= I_A;
;         if (r < I_B) { p0_transpose_item<false>(P.wb, 512, 1024, (u16*)(P.ws + WS_WB), scr, r, lane); continue; } r -= I_B;
;         p0_transpose_item<false>(P.wo, 1024, 1024, (u16*)(P.ws + WS_WO), scr, r, lane);
.LBB0_24:
	s_cmpk_gt_i32 s28, 0x15ff
	s_mov_b64 s[8:9], -1
	s_cbranch_scc0 .LBB0_34
	s_cmpk_gt_u32 s28, 0x17ff
	s_cbranch_scc0 .LBB0_31
	s_cmpk_gt_u32 s28, 0x18ff
	s_cbranch_scc0 .LBB0_28
	s_add_i32 s8, s18, 0xfffce000
	s_and_b32 s8, s8, 0x3e0
	s_and_b32 s9, s21, 0xf0000
	s_or_b32 s9, s9, s8
	v_or_b32_e32 v0, s9, v26
	v_or_b32_e32 v14, s9, v29
	v_or_b32_e32 v15, s9, v30
	v_or_b32_e32 v16, s9, v31
	v_or_b32_e32 v17, s9, v32
	v_or_b32_e32 v18, s9, v33
	v_lshlrev_b32_e32 v0, 2, v0
	v_or_b32_e32 v12, s9, v27
	v_or_b32_e32 v13, s9, v28
	v_lshlrev_b32_e32 v14, 2, v14
	v_lshlrev_b32_e32 v15, 2, v15
	v_lshlrev_b32_e32 v16, 2, v16
	v_lshlrev_b32_e32 v17, 2, v17
	v_lshlrev_b32_e32 v18, 2, v18
	v_lshlrev_b32_e32 v12, 2, v12
	v_lshlrev_b32_e32 v13, 2, v13
	global_load_dword v19, v0, s[72:73] nt
	global_load_dword v20, v12, s[72:73] nt
	global_load_dword v21, v13, s[72:73] nt
	s_nop 0
	global_load_dword v14, v14, s[72:73] nt
	s_nop 0
	global_load_dword v15, v15, s[72:73] nt
	s_nop 0
	global_load_dword v16, v16, s[72:73] nt
	s_nop 0
	global_load_dword v17, v17, s[72:73] nt
	s_nop 0
	global_load_dword v18, v18, s[72:73] nt
	v_or_b32_e32 v0, s9, v34
	v_or_b32_e32 v22, s9, v37
	v_or_b32_e32 v23, s9, v38
	v_or_b32_e32 v71, s9, v39
	v_or_b32_e32 v72, s9, v40
	v_or_b32_e32 v73, s9, v41
	v_lshlrev_b32_e32 v0, 2, v0
	v_or_b32_e32 v12, s9, v35
	v_or_b32_e32 v13, s9, v36
	v_lshlrev_b32_e32 v22, 2, v22
	v_lshlrev_b32_e32 v23, 2, v23
	v_lshlrev_b32_e32 v71, 2, v71
	v_lshlrev_b32_e32 v72, 2, v72
	v_lshlrev_b32_e32 v73, 2, v73
	v_lshlrev_b32_e32 v12, 2, v12
	v_lshlrev_b32_e32 v13, 2, v13
	global_load_dword v74, v0, s[72:73] nt
	global_load_dword v75, v12, s[72:73] nt
	global_load_dword v76, v13, s[72:73] nt
	s_nop 0
	global_load_dword v22, v22, s[72:73] nt
	s_nop 0
	global_load_dword v23, v23, s[72:73] nt
	s_nop 0
	global_load_dword v71, v71, s[72:73] nt
	s_nop 0
	global_load_dword v72, v72, s[72:73] nt
	s_nop 0
	global_load_dword v73, v73, s[72:73] nt
	v_or_b32_e32 v0, s9, v42
	v_or_b32_e32 v77, s9, v45
	v_or_b32_e32 v78, s9, v46
	v_or_b32_e32 v79, s9, v47
	v_or_b32_e32 v80, s9, v48
	v_or_b32_e32 v81, s9, v49
	v_lshlrev_b32_e32 v0, 2, v0
	v_or_b32_e32 v12, s9, v43
	v_or_b32_e32 v13, s9, v44
	v_lshlrev_b32_e32 v77, 2, v77
	v_lshlrev_b32_e32 v78, 2, v78
	v_lshlrev_b32_e32 v79, 2, v79
	v_lshlrev_b32_e32 v80, 2, v80
	v_lshlrev_b32_e32 v81, 2, v81
	v_lshlrev_b32_e32 v12, 2, v12
	v_lshlrev_b32_e32 v13, 2, v13
	global_load_dword v82, v0, s[72:73] nt
	global_load_dword v83, v12, s[72:73] nt
	global_load_dword v84, v13, s[72:73] nt
	s_nop 0
	global_load_dword v77, v77, s[72:73] nt
	s_nop 0
	global_load_dword v78, v78, s[72:73] nt
	s_nop 0
	global_load_dword v79, v79, s[72:73] nt
	s_nop 0
	global_load_dword v80, v80, s[72:73] nt
	s_nop 0
	global_load_dword v81, v81, s[72:73] nt
	v_or_b32_e32 v0, s9, v50
	v_lshlrev_b32_e32 v85, 2, v0
	v_or_b32_e32 v0, s9, v51
	v_lshlrev_b32_e32 v86, 2, v0
	v_or_b32_e32 v0, s9, v52
	v_lshlrev_b32_e32 v87, 2, v0
	v_or_b32_e32 v0, s9, v53
	v_lshlrev_b32_e32 v88, 2, v0
	v_or_b32_e32 v0, s9, v54
	s_and_b32 s6, s20, 0x3e0
	v_lshlrev_b32_e32 v89, 2, v0
	v_or_b32_e32 v0, s9, v55
	v_lshlrev_b32_e32 v90, 2, v0
	v_or_b32_e32 v0, s9, v56
	s_add_i32 s6, s6, s21
	v_lshlrev_b32_e32 v91, 2, v0
	v_add_u32_e32 v0, s6, v26
	v_or_b32_e32 v0, 0xf800, v0
	v_lshl_add_u64 v[12:13], v[0:1], 2, s[72:73]
	global_load_dword v0, v85, s[72:73] nt
	s_nop 0
	global_load_dword v85, v86, s[72:73] nt
	s_nop 0
	global_load_dword v86, v87, s[72:73] nt
	s_nop 0
	global_load_dword v87, v88, s[72:73] nt
	s_nop 0
	global_load_dword v88, v89, s[72:73] nt
	s_nop 0
	global_load_dword v89, v90, s[72:73] nt
	s_nop 0
	global_load_dword v90, v91, s[72:73] nt
	s_nop 0
	global_load_dword v12, v[12:13], off nt
	s_and_b32 s6, s23, 0x3c0
	s_lshl_b32 s6, s6, 1
	s_waitcnt vmcnt(30)
	ds_write2_b32 v62, v19, v20 offset1:66
	s_waitcnt vmcnt(28)
	ds_write2_b32 v62, v21, v14 offset0:132 offset1:198
	s_waitcnt vmcnt(26)
	ds_write2_b32 v64, v15, v16 offset0:8 offset1:74
	s_waitcnt vmcnt(24)
	ds_write2_b32 v64, v17, v18 offset0:140 offset1:206
	s_waitcnt vmcnt(22)
	ds_write2_b32 v65, v74, v75 offset0:16 offset1:82
	s_waitcnt vmcnt(20)
	ds_write2_b32 v65, v76, v22 offset0:148 offset1:214
	s_waitcnt vmcnt(18)
	ds_write2_b32 v66, v23, v71 offset0:24 offset1:90
	s_waitcnt vmcnt(16)
	ds_write2_b32 v66, v72, v73 offset0:156 offset1:222
	s_waitcnt vmcnt(14)
	ds_write2_b32 v67, v82, v83 offset0:32 offset1:98
	s_waitcnt vmcnt(12)
	ds_write2_b32 v67, v84, v77 offset0:164 offset1:230
	s_waitcnt vmcnt(10)
	ds_write2_b32 v68, v78, v79 offset0:40 offset1:106
	s_waitcnt vmcnt(8)
	ds_write2_b32 v68, v80, v81 offset0:172 offset1:238
	s_waitcnt vmcnt(6)
	ds_write2_b32 v69, v0, v85 offset0:48 offset1:114
	s_waitcnt vmcnt(4)
	ds_write2_b32 v69, v86, v87 offset0:180 offset1:246
	s_waitcnt vmcnt(2)
	ds_write2_b32 v70, v88, v89 offset0:56 offset1:122
	s_waitcnt vmcnt(0)
	ds_write2_b32 v70, v90, v12 offset0:188 offset1:254
	s_waitcnt lgkmcnt(0)
	ds_read2_b32 v[16:17], v63 offset0:33 offset1:41
	ds_read2_b32 v[18:19], v63 offset1:8
	ds_read2_b32 v[20:21], v63 offset0:66 offset1:74
	ds_read2_b32 v[22:23], v63 offset0:99 offset1:107
	ds_read2_b32 v[72:73], v63 offset0:132 offset1:140
	ds_read2_b32 v[74:75], v63 offset0:165 offset1:173
	ds_read2_b32 v[76:77], v63 offset0:198 offset1:206
	ds_read2_b32 v[78:79], v63 offset0:231 offset1:239
	v_or_b32_e32 v0, s8, v58
	v_lshl_add_u64 v[80:81], v[6:7], 0, s[6:7]
	v_lshlrev_b32_e32 v0, 11, v0
	s_waitcnt lgkmcnt(6)
	v_cvt_pk_bf16_f32 v12, v18, v16
	s_waitcnt lgkmcnt(4)
	v_cvt_pk_bf16_f32 v13, v20, v22
	s_waitcnt lgkmcnt(2)
	v_cvt_pk_bf16_f32 v14, v72, v74
	s_waitcnt lgkmcnt(0)
; #define LAS __attribute__((address_space(3)))
; __device__ __forceinline__ unsigned pk_bf16(float lo, float hi) { typedef __bf16 b2 __attribute__((ext_vector_type(2))); f32x2 v = {lo, hi}; b2 b = __builtin_convertvector(v, b2); return __builtin_bit_cast(unsigned, b); }
; template <bool MAP> __device__ __forceinline__ void p0_transpose_item(const float* W, int K, int N, u16* WT, LAS float* scr, int item, int lane) {
;     const int nblk = N / 32, kb = item / nblk, nb = item % nblk, k0 = 64 * kb, n0 = 32 * nb;
;     float tv[32];
; #pragma unroll
;     for (int i = 0; i < 32; ++i) tv[i] = W[(size_t)(k0 + 2 * i + (lane >> 5)) * N + n0 + (lane & 31)];
; #pragma unroll
;     for (int i = 0; i < 32; ++i) scr[(2 * i + (lane >> 5)) * 33 + (lane & 31)] = tv[i];
;     asm volatile("s_waitcnt lgkmcnt(0)" ::: "memory");
;     const int c = lane & 7;
; #pragma unroll
;     for (int j = 0; j < 4; ++j) { const int n = (lane >> 3) + 8 * j; const LAS float* s = scr + (8 * c) * 33 + n;
;         u32x4 o; o.x = pk_bf16(s[0 * 33], s[1 * 33]); o.y = pk_bf16(s[2 * 33], s[3 * 33]); o.z = pk_bf16(s[4 * 33], s[5 * 33]); o.w = pk_bf16(s[6 * 33], s[7 * 33]);
;         const int r = MAP ? wt_row_of_col(n0 + n) : (n0 + n);
;         *(u32x4*)(WT + (size_t)r * K + k0 + 8 * c) = o; }
	v_cvt_pk_bf16_f32 v15, v76, v78
	v_lshl_add_u64 v[82:83], v[80:81], 0, v[0:1]
	global_store_dwordx4 v[82:83], v[12:15], off sc0 sc1
	v_or_b32_e32 v0, s8, v59
	v_lshlrev_b32_e32 v0, 11, v0
	v_cvt_pk_bf16_f32 v12, v19, v17
	v_cvt_pk_bf16_f32 v13, v21, v23
	v_cvt_pk_bf16_f32 v14, v73, v75
	v_cvt_pk_bf16_f32 v15, v77, v79
	ds_read2_b32 v[18:19], v63 offset0:49 offset1:57
	ds_read2_b32 v[20:21], v63 offset0:16 offset1:24
	ds_read2_b32 v[22:23], v63 offset0:82 offset1:90
	ds_read2_b32 v[72:73], v63 offset0:115 offset1:123
	ds_read2_b32 v[74:75], v63 offset0:148 offset1:156
	ds_read2_b32 v[76:77], v63 offset0:181 offset1:189
	ds_read2_b32 v[78:79], v63 offset0:214 offset1:222
	ds_read2_b32 v[82:83], v63 offset0:247 offset1:255
	v_lshl_add_u64 v[16:17], v[80:81], 0, v[0:1]
	v_or_b32_e32 v0, s8, v60
	v_lshlrev_b32_e32 v0, 11, v0
	global_store_dwordx4 v[16:17], v[12:15], off sc0 sc1
	v_lshl_add_u64 v[16:17], v[80:81], 0, v[0:1]
	v_or_b32_e32 v0, s8, v61
	s_waitcnt lgkmcnt(6)
	v_cvt_pk_bf16_f32 v12, v20, v18
	s_waitcnt lgkmcnt(4)
	v_cvt_pk_bf16_f32 v13, v22, v72
	s_waitcnt lgkmcnt(2)
	v_cvt_pk_bf16_f32 v14, v74, v76
	s_waitcnt lgkmcnt(0)
	v_cvt_pk_bf16_f32 v15, v78, v82
	v_lshlrev_b32_e32 v0, 11, v0
	global_store_dwordx4 v[16:17], v[12:15], off sc0 sc1
	v_lshl_add_u64 v[16:17], v[80:81], 0, v[0:1]
	s_mov_b64 s[8:9], 0
	v_cvt_pk_bf16_f32 v12, v21, v19
	v_cvt_pk_bf16_f32 v13, v23, v73
	v_cvt_pk_bf16_f32 v14, v75, v77
	v_cvt_pk_bf16_f32 v15, v79, v83
	global_store_dwordx4 v[16:17], v[12:15], off sc0 sc1
	s_waitcnt lgkmcnt(0)
.LBB0_28:
	s_andn2_b64 vcc, exec, s[8:9]
	s_cbranch_vccnz .LBB0_30
	s_add_i32 s8, s18, 0xfffd0000
	s_add_i32 s9, s21, 0xc80000
	s_and_b32 s8, s8, 0x3e0
	s_and_b32 s9, s9, 0xf0000
	s_or_b32 s9, s8, s9
	v_or_b32_e32 v0, s9, v26
	v_or_b32_e32 v14, s9, v29
	v_or_b32_e32 v15, s9, v30
	v_or_b32_e32 v16, s9, v31
	v_or_b32_e32 v17, s9, v32
	v_or_b32_e32 v18, s9, v33
	v_lshlrev_b32_e32 v0, 2, v0
	v_or_b32_e32 v12, s9, v27
	v_or_b32_e32 v13, s9, v28
	v_lshlrev_b32_e32 v14, 2, v14
	v_lshlrev_b32_e32 v15, 2, v15
	v_lshlrev_b32_e32 v16, 2, v16
	v_lshlrev_b32_e32 v17, 2, v17
	v_lshlrev_b32_e32 v18, 2, v18
	v_lshlrev_b32_e32 v12, 2, v12
	v_lshlrev_b32_e32 v13, 2, v13
	global_load_dword v19, v0, s[70:71] nt
	global_load_dword v20, v12, s[70:71] nt
	global_load_dword v21, v13, s[70:71] nt
	s_nop 0
	global_load_dword v14, v14, s[70:71] nt
	s_nop 0
	global_load_dword v15, v15, s[70:71] nt
	s_nop 0
	global_load_dword v16, v16, s[70:71] nt
	s_nop 0
	global_load_dword v17, v17, s[70:71] nt
	s_nop 0
	global_load_dword v18, v18, s[70:71] nt
	v_or_b32_e32 v0, s9, v34
	v_or_b32_e32 v22, s9, v37
	v_or_b32_e32 v23, s9, v38
	v_or_b32_e32 v71, s9, v39
	v_or_b32_e32 v72, s9, v40
	v_or_b32_e32 v73, s9, v41
	v_lshlrev_b32_e32 v0, 2, v0
	v_or_b32_e32 v12, s9, v35
	v_or_b32_e32 v13, s9, v36
	v_lshlrev_b32_e32 v22, 2, v22
	v_lshlrev_b32_e32 v23, 2, v23
	v_lshlrev_b32_e32 v71, 2, v71
	v_lshlrev_b32_e32 v72, 2, v72
	v_lshlrev_b32_e32 v73, 2, v73
	v_lshlrev_b32_e32 v12, 2, v12
	v_lshlrev_b32_e32 v13, 2, v13
	global_load_dword v74, v0, s[70:71] nt
	global_load_dword v75, v12, s[70:71] nt
	global_load_dword v76, v13, s[70:71] nt
	s_nop 0
	global_load_dword v22, v22, s[70:71] nt
	s_nop 0
	global_load_dword v23, v23, s[70:71] nt
	s_nop 0
	global_load_dword v71, v71, s[70:71] nt
	s_nop 0
	global_load_dword v72, v72, s[70:71] nt
	s_nop 0
	global_load_dword v73, v73, s[70:71] nt
	v_or_b32_e32 v0, s9, v42
	v_or_b32_e32 v77, s9, v45
	v_or_b32_e32 v78, s9, v46
	v_or_b32_e32 v79, s9, v47
	v_or_b32_e32 v80, s9, v48
	v_or_b32_e32 v81, s9, v49
	v_lshlrev_b32_e32 v0, 2, v0
	v_or_b32_e32 v12, s9, v43
	v_or_b32_e32 v13, s9, v44
	v_lshlrev_b32_e32 v77, 2, v77
	v_lshlrev_b32_e32 v78, 2, v78
	v_lshlrev_b32_e32 v79, 2, v79
	v_lshlrev_b32_e32 v80, 2, v80
	v_lshlrev_b32_e32 v81, 2, v81
	v_lshlrev_b32_e32 v12, 2, v12
	v_lshlrev_b32_e32 v13, 2, v13
	global_load_dword v82, v0, s[70:71] nt
	global_load_dword v83, v12, s[70:71] nt
	global_load_dword v84, v13, s[70:71] nt
	s_nop 0
	global_load_dword v77, v77, s[70:71] nt
	s_nop 0
	global_load_dword v78, v78, s[70:71] nt
	s_nop 0
	global_load_dword v79, v79, s[70:71] nt
	s_nop 0
	global_load_dword v80, v80, s[70:71] nt
	s_nop 0
	global_load_dword v81, v81, s[70:71] nt
	v_or_b32_e32 v0, s9, v50
	v_lshlrev_b32_e32 v85, 2, v0
	v_or_b32_e32 v0, s9, v51
	v_lshlrev_b32_e32 v86, 2, v0
	v_or_b32_e32 v0, s9, v52
	v_lshlrev_b32_e32 v87, 2, v0
	v_or_b32_e32 v0, s9, v53
	v_lshlrev_b32_e32 v88, 2, v0
	v_or_b32_e32 v0, s9, v54
	s_and_b32 s6, s25, 0x3e0
	v_lshlrev_b32_e32 v89, 2, v0
	v_or_b32_e32 v0, s9, v55
	v_lshlrev_b32_e32 v90, 2, v0
	v_or_b32_e32 v0, s9, v56
	s_add_i32 s6, s6, s21
	v_lshlrev_b32_e32 v91, 2, v0
	v_add_u32_e32 v0, s6, v26
	v_add_u32_e32 v0, 0x80000, v0
	v_or_b32_e32 v0, 0xf800, v0
	v_lshl_add_u64 v[12:13], v[0:1], 2, s[70:71]
	global_load_dword v0, v85, s[70:71] nt
	s_nop 0
	global_load_dword v85, v86, s[70:71] nt
	s_nop 0
	global_load_dword v86, v87, s[70:71] nt
	s_nop 0
	global_load_dword v87, v88, s[70:71] nt
	s_nop 0
	global_load_dword v88, v89, s[70:71] nt
	s_nop 0
	global_load_dword v89, v90, s[70:71] nt
	s_nop 0
	global_load_dword v90, v91, s[70:71] nt
	s_nop 0
	global_load_dword v12, v[12:13], off nt
	s_add_i32 s6, s23, 0x200
	s_and_b32 s6, s6, 0x3c0
	s_lshl_b32 s6, s6, 1
	s_waitcnt vmcnt(30)
; #define LAS __attribute__((address_space(3)))
; __device__ __forceinline__ unsigned pk_bf16(float lo, float hi) { typedef __bf16 b2 __attribute__((ext_vector_type(2))); f32x2 v = {lo, hi}; b2 b = __builtin_convertvector(v, b2); return __builtin_bit_cast(unsigned, b); }
; template <bool MAP> __device__ __forceinline__ void p0_transpose_item(const float* W, int K, int N, u16* WT, LAS float* scr, int item, int lane) {
;     const int nblk = N / 32, kb = item / nblk, nb = item % nblk, k0 = 64 * kb, n0 = 32 * nb;
;     float tv[32];
; #pragma unroll
;     for (int i = 0; i < 32; ++i) tv[i] = W[(size_t)(k0 + 2 * i + (lane >> 5)) * N + n0 + (lane & 31)];
; #pragma unroll
;     for (int i = 0; i < 32; ++i) scr[(2 * i + (lane >> 5)) * 33 + (lane & 31)] = tv[i];
;     asm volatile("s_waitcnt lgkmcnt(0)" ::: "memory");
;     const int c = lane & 7;
; #pragma unroll
;     for (int j = 0; j < 4; ++j) { const int n = (lane >> 3) + 8 * j; const LAS float* s = scr + (8 * c) * 33 + n;
;         u32x4 o; o.x = pk_bf16(s[0 * 33], s[1 * 33]); o.y = pk_bf16(s[2 * 33], s[3 * 33]); o.z = pk_bf16(s[4 * 33], s[5 * 33]); o.w = pk_bf16(s[6 * 33], s[7 * 33]);
;         const int r = MAP ? wt_row_of_col(n0 + n) : (n0 + n);
;         *(u32x4*)(WT + (size_t)r * K + k0 + 8 * c) = o; }
	ds_write2_b32 v62, v19, v20 offset1:66
	s_waitcnt vmcnt(28)
	ds_write2_b32 v62, v21, v14 offset0:132 offset1:198
	s_waitcnt vmcnt(26)
	ds_write2_b32 v64, v15, v16 offset0:8 offset1:74
	s_waitcnt vmcnt(24)
	ds_write2_b32 v64, v17, v18 offset0:140 offset1:206
	s_waitcnt vmcnt(22)
	ds_write2_b32 v65, v74, v75 offset0:16 offset1:82
	s_waitcnt vmcnt(20)
	ds_write2_b32 v65, v76, v22 offset0:148 offset1:214
	s_waitcnt vmcnt(18)
	ds_write2_b32 v66, v23, v71 offset0:24 offset1:90
	s_waitcnt vmcnt(16)
	ds_write2_b32 v66, v72, v73 offset0:156 offset1:222
	s_waitcnt vmcnt(14)
	ds_write2_b32 v67, v82, v83 offset0:32 offset1:98
	s_waitcnt vmcnt(12)
	ds_write2_b32 v67, v84, v77 offset0:164 offset1:230
	s_waitcnt vmcnt(10)
	ds_write2_b32 v68, v78, v79 offset0:40 offset1:106
	s_waitcnt vmcnt(8)
	ds_write2_b32 v68, v80, v81 offset0:172 offset1:238
	s_waitcnt vmcnt(6)
	ds_write2_b32 v69, v0, v85 offset0:48 offset1:114
	s_waitcnt vmcnt(4)
	ds_write2_b32 v69, v86, v87 offset0:180 offset1:246
	s_waitcnt vmcnt(2)
	ds_write2_b32 v70, v88, v89 offset0:56 offset1:122
	s_waitcnt vmcnt(0)
	ds_write2_b32 v70, v90, v12 offset0:188 offset1:254
	s_waitcnt lgkmcnt(0)
	ds_read2_b32 v[16:17], v63 offset0:33 offset1:41
	ds_read2_b32 v[18:19], v63 offset1:8
	ds_read2_b32 v[20:21], v63 offset0:66 offset1:74
	ds_read2_b32 v[22:23], v63 offset0:99 offset1:107
	ds_read2_b32 v[72:73], v63 offset0:132 offset1:140
	ds_read2_b32 v[74:75], v63 offset0:165 offset1:173
	ds_read2_b32 v[76:77], v63 offset0:198 offset1:206
	ds_read2_b32 v[78:79], v63 offset0:231 offset1:239
	v_or_b32_e32 v0, s8, v58
	v_lshl_add_u64 v[80:81], v[8:9], 0, s[6:7]
	v_lshlrev_b32_e32 v0, 10, v0
	s_waitcnt lgkmcnt(6)
	v_cvt_pk_bf16_f32 v12, v18, v16
	s_waitcnt lgkmcnt(4)
	v_cvt_pk_bf16_f32 v13, v20, v22
	s_waitcnt lgkmcnt(2)
	v_cvt_pk_bf16_f32 v14, v72, v74
	s_waitcnt lgkmcnt(0)
	v_cvt_pk_bf16_f32 v15, v76, v78
	v_lshl_add_u64 v[82:83], v[80:81], 0, v[0:1]
	global_store_dwordx4 v[82:83], v[12:15], off sc0 sc1
	v_or_b32_e32 v0, s8, v59
	v_lshlrev_b32_e32 v0, 10, v0
	v_cvt_pk_bf16_f32 v12, v19, v17
	v_cvt_pk_bf16_f32 v13, v21, v23
	v_cvt_pk_bf16_f32 v14, v73, v75
	v_cvt_pk_bf16_f32 v15, v77, v79
	ds_read2_b32 v[18:19], v63 offset0:49 offset1:57
	ds_read2_b32 v[20:21], v63 offset0:16 offset1:24
	ds_read2_b32 v[22:23], v63 offset0:82 offset1:90
	ds_read2_b32 v[72:73], v63 offset0:115 offset1:123
	ds_read2_b32 v[74:75], v63 offset0:148 offset1:156
	ds_read2_b32 v[76:77], v63 offset0:181 offset1:189
	ds_read2_b32 v[78:79], v63 offset0:214 offset1:222
	ds_read2_b32 v[82:83], v63 offset0:247 offset1:255
	v_lshl_add_u64 v[16:17], v[80:81], 0, v[0:1]
	v_or_b32_e32 v0, s8, v60
	v_lshlrev_b32_e32 v0, 10, v0
	global_store_dwordx4 v[16:17], v[12:15], off sc0 sc1
	v_lshl_add_u64 v[16:17], v[80:81], 0, v[0:1]
	v_or_b32_e32 v0, s8, v61
	s_waitcnt lgkmcnt(6)
	v_cvt_pk_bf16_f32 v12, v20, v18
	s_waitcnt lgkmcnt(4)
	v_cvt_pk_bf16_f32 v13, v22, v72
	s_waitcnt lgkmcnt(2)
	v_cvt_pk_bf16_f32 v14, v74, v76
	s_waitcnt lgkmcnt(0)
	v_cvt_pk_bf16_f32 v15, v78, v82
	v_lshlrev_b32_e32 v0, 10, v0
	global_store_dwordx4 v[16:17], v[12:15], off sc0 sc1
	v_lshl_add_u64 v[16:17], v[80:81], 0, v[0:1]
	s_nop 0
	v_cvt_pk_bf16_f32 v12, v21, v19
	v_cvt_pk_bf16_f32 v13, v23, v73
	v_cvt_pk_bf16_f32 v14, v75, v77
	v_cvt_pk_bf16_f32 v15, v79, v83
	global_store_dwordx4 v[16:17], v[12:15], off sc0 sc1
	s_waitcnt lgkmcnt(0)

; #define LAS __attribute__((address_space(3)))
; template <bool MAP> __device__ __forceinline__ void p0_transpose_item(const float* W, int K, int N, u16* WT, LAS float* scr, int item, int lane) {
;     const int nblk = N / 32, kb = item / nblk, nb = item % nblk, k0 = 64 * kb, n0 = 32 * nb;
;     float tv[32];
; #pragma unroll
;     for (int i = 0; i < 32; ++i) tv[i] = W[(size_t)(k0 + 2 * i + (lane >> 5)) * N + n0 + (lane & 31)];
; #pragma unroll
;     for (int i = 0; i < 32; ++i) scr[(2 * i + (lane >> 5)) * 33 + (lane & 31)] = tv[i];
.LBB0_31:
	s_andn2_b64 vcc, exec, s[8:9]
	s_cbranch_vccnz .LBB0_33
	s_add_i32 s8, s18, 0xfffd4000
	s_add_i32 s9, s21, 0xc80000
	s_and_b32 s8, s8, 0x3e0
	s_and_b32 s9, s9, 0xf0000
	s_or_b32 s9, s8, s9
	v_or_b32_e32 v0, s9, v26
	v_or_b32_e32 v14, s9, v29
	v_or_b32_e32 v15, s9, v30
	v_or_b32_e32 v16, s9, v31
	v_or_b32_e32 v17, s9, v32
	v_or_b32_e32 v18, s9, v33
	v_lshlrev_b32_e32 v0, 2, v0
	v_or_b32_e32 v12, s9, v27
	v_or_b32_e32 v13, s9, v28
	v_lshlrev_b32_e32 v14, 2, v14
	v_lshlrev_b32_e32 v15, 2, v15
	v_lshlrev_b32_e32 v16, 2, v16
	v_lshlrev_b32_e32 v17, 2, v17
	v_lshlrev_b32_e32 v18, 2, v18
	v_lshlrev_b32_e32 v12, 2, v12
	v_lshlrev_b32_e32 v13, 2, v13
	global_load_dword v19, v0, s[68:69] nt
	global_load_dword v20, v12, s[68:69] nt
	global_load_dword v21, v13, s[68:69] nt
	s_nop 0
	global_load_dword v14, v14, s[68:69] nt
	s_nop 0
	global_load_dword v15, v15, s[68:69] nt
	s_nop 0
	global_load_dword v16, v16, s[68:69] nt
	s_nop 0
	global_load_dword v17, v17, s[68:69] nt
	s_nop 0
	global_load_dword v18, v18, s[68:69] nt
	v_or_b32_e32 v0, s9, v34
	v_or_b32_e32 v22, s9, v37
	v_or_b32_e32 v23, s9, v38
	v_or_b32_e32 v71, s9, v39
	v_or_b32_e32 v72, s9, v40
	v_or_b32_e32 v73, s9, v41
	v_lshlrev_b32_e32 v0, 2, v0
	v_or_b32_e32 v12, s9, v35
	v_or_b32_e32 v13, s9, v36
	v_lshlrev_b32_e32 v22, 2, v22
	v_lshlrev_b32_e32 v23, 2, v23
	v_lshlrev_b32_e32 v71, 2, v71
	v_lshlrev_b32_e32 v72, 2, v72
	v_lshlrev_b32_e32 v73, 2, v73
	v_lshlrev_b32_e32 v12, 2, v12
	v_lshlrev_b32_e32 v13, 2, v13
	global_load_dword v74, v0, s[68:69] nt
	global_load_dword v75, v12, s[68:69] nt
	global_load_dword v76, v13, s[68:69] nt
	s_nop 0
	global_load_dword v22, v22, s[68:69] nt
	s_nop 0
	global_load_dword v23, v23, s[68:69] nt
	s_nop 0
	global_load_dword v71, v71, s[68:69] nt
	s_nop 0
	global_load_dword v72, v72, s[68:69] nt
	s_nop 0
	global_load_dword v73, v73, s[68:69] nt
	v_or_b32_e32 v0, s9, v42
	v_or_b32_e32 v77, s9, v45
	v_or_b32_e32 v78, s9, v46
	v_or_b32_e32 v79, s9, v47
	v_or_b32_e32 v80, s9, v48
	v_or_b32_e32 v81, s9, v49
	v_lshlrev_b32_e32 v0, 2, v0
	v_or_b32_e32 v12, s9, v43
	v_or_b32_e32 v13, s9, v44
	v_lshlrev_b32_e32 v77, 2, v77
	v_lshlrev_b32_e32 v78, 2, v78
	v_lshlrev_b32_e32 v79, 2, v79
	v_lshlrev_b32_e32 v80, 2, v80
	v_lshlrev_b32_e32 v81, 2, v81
	v_lshlrev_b32_e32 v12, 2, v12
	v_lshlrev_b32_e32 v13, 2, v13
	global_load_dword v82, v0, s[68:69] nt
	global_load_dword v83, v12, s[68:69] nt
	global_load_dword v84, v13, s[68:69] nt
	s_nop 0
	global_load_dword v77, v77, s[68:69] nt
	s_nop 0
	global_load_dword v78, v78, s[68:69] nt
	s_nop 0
	global_load_dword v79, v79, s[68:69] nt
	s_nop 0
	global_load_dword v80, v80, s[68:69] nt
	s_nop 0
	global_load_dword v81, v81, s[68:69] nt
	v_or_b32_e32 v0, s9, v50
	v_lshlrev_b32_e32 v85, 2, v0
	v_or_b32_e32 v0, s9, v51
	v_lshlrev_b32_e32 v86, 2, v0
	v_or_b32_e32 v0, s9, v52
	v_lshlrev_b32_e32 v87, 2, v0
	v_or_b32_e32 v0, s9, v53
	v_lshlrev_b32_e32 v88, 2, v0
	v_or_b32_e32 v0, s9, v54
	s_and_b32 s6, s26, 0x3e0
	v_lshlrev_b32_e32 v89, 2, v0
	v_or_b32_e32 v0, s9, v55
	v_lshlrev_b32_e32 v90, 2, v0
	v_or_b32_e32 v0, s9, v56
	s_add_i32 s6, s6, s21
	v_lshlrev_b32_e32 v91, 2, v0
	v_add_u32_e32 v0, s6, v26
	v_add_u32_e32 v0, 0x180000, v0
	v_or_b32_e32 v0, 0xf800, v0
	v_lshl_add_u64 v[12:13], v[0:1], 2, s[68:69]
	global_load_dword v0, v85, s[68:69] nt
	s_nop 0
	global_load_dword v85, v86, s[68:69] nt
	s_nop 0
	global_load_dword v86, v87, s[68:69] nt
	s_nop 0
	global_load_dword v87, v88, s[68:69] nt
	s_nop 0
	global_load_dword v88, v89, s[68:69] nt
	s_nop 0
	global_load_dword v89, v90, s[68:69] nt
	s_nop 0
	global_load_dword v90, v91, s[68:69] nt
	s_nop 0
	global_load_dword v12, v[12:13], off nt
	s_add_i32 s6, s23, 0x600
	s_and_b32 s6, s6, 0x3c0
	s_lshl_b32 s6, s6, 1
	s_waitcnt vmcnt(30)
; #define LAS __attribute__((address_space(3)))
; __device__ __forceinline__ unsigned pk_bf16(float lo, float hi) { typedef __bf16 b2 __attribute__((ext_vector_type(2))); f32x2 v = {lo, hi}; b2 b = __builtin_convertvector(v, b2); return __builtin_bit_cast(unsigned, b); }
; template <bool MAP> __device__ __forceinline__ void p0_transpose_item(const float* W, int K, int N, u16* WT, LAS float* scr, int item, int lane) {
;     const int nblk = N / 32, kb = item / nblk, nb = item % nblk, k0 = 64 * kb, n0 = 32 * nb;
;     float tv[32];
; #pragma unroll
;     for (int i = 0; i < 32; ++i) tv[i] = W[(size_t)(k0 + 2 * i + (lane >> 5)) * N + n0 + (lane & 31)];
; #pragma unroll
;     for (int i = 0; i < 32; ++i) scr[(2 * i + (lane >> 5)) * 33 + (lane & 31)] = tv[i];
;     asm volatile("s_waitcnt lgkmcnt(0)" ::: "memory");
;     const int c = lane & 7;
; #pragma unroll
;     for (int j = 0; j < 4; ++j) { const int n = (lane >> 3) + 8 * j; const LAS float* s = scr + (8 * c) * 33 + n;
;         u32x4 o; o.x = pk_bf16(s[0 * 33], s[1 * 33]); o.y = pk_bf16(s[2 * 33], s[3 * 33]); o.z = pk_bf16(s[4 * 33], s[5 * 33]); o.w = pk_bf16(s[6 * 33], s[7 * 33]);
;         const int r = MAP ? wt_row_of_col(n0 + n) : (n0 + n);
;         *(u32x4*)(WT + (size_t)r * K + k0 + 8 * c) = o; }
	ds_write2_b32 v62, v19, v20 offset1:66
	s_waitcnt vmcnt(28)
	ds_write2_b32 v62, v21, v14 offset0:132 offset1:198
	s_waitcnt vmcnt(26)
	ds_write2_b32 v64, v15, v16 offset0:8 offset1:74
	s_waitcnt vmcnt(24)
	ds_write2_b32 v64, v17, v18 offset0:140 offset1:206
	s_waitcnt vmcnt(22)
	ds_write2_b32 v65, v74, v75 offset0:16 offset1:82
	s_waitcnt vmcnt(20)
	ds_write2_b32 v65, v76, v22 offset0:148 offset1:214
	s_waitcnt vmcnt(18)
	ds_write2_b32 v66, v23, v71 offset0:24 offset1:90
	s_waitcnt vmcnt(16)
	ds_write2_b32 v66, v72, v73 offset0:156 offset1:222
	s_waitcnt vmcnt(14)
	ds_write2_b32 v67, v82, v83 offset0:32 offset1:98
	s_waitcnt vmcnt(12)
	ds_write2_b32 v67, v84, v77 offset0:164 offset1:230
	s_waitcnt vmcnt(10)
	ds_write2_b32 v68, v78, v79 offset0:40 offset1:106
	s_waitcnt vmcnt(8)
	ds_write2_b32 v68, v80, v81 offset0:172 offset1:238
	s_waitcnt vmcnt(6)
	ds_write2_b32 v69, v0, v85 offset0:48 offset1:114
	s_waitcnt vmcnt(4)
	ds_write2_b32 v69, v86, v87 offset0:180 offset1:246
	s_waitcnt vmcnt(2)
	ds_write2_b32 v70, v88, v89 offset0:56 offset1:122
	s_waitcnt vmcnt(0)
	ds_write2_b32 v70, v90, v12 offset0:188 offset1:254
	s_waitcnt lgkmcnt(0)
	ds_read2_b32 v[16:17], v63 offset0:33 offset1:41
	ds_read2_b32 v[18:19], v63 offset1:8
	ds_read2_b32 v[20:21], v63 offset0:66 offset1:74
	ds_read2_b32 v[22:23], v63 offset0:99 offset1:107
	ds_read2_b32 v[72:73], v63 offset0:132 offset1:140
	ds_read2_b32 v[74:75], v63 offset0:165 offset1:173
	ds_read2_b32 v[76:77], v63 offset0:198 offset1:206
	ds_read2_b32 v[78:79], v63 offset0:231 offset1:239
	v_or_b32_e32 v0, s8, v58
	v_lshl_add_u64 v[80:81], v[10:11], 0, s[6:7]
	v_lshlrev_b32_e32 v0, 11, v0
	s_waitcnt lgkmcnt(6)
	v_cvt_pk_bf16_f32 v12, v18, v16
	s_waitcnt lgkmcnt(4)
	v_cvt_pk_bf16_f32 v13, v20, v22
	s_waitcnt lgkmcnt(2)
	v_cvt_pk_bf16_f32 v14, v72, v74
	s_waitcnt lgkmcnt(0)
	v_cvt_pk_bf16_f32 v15, v76, v78
	v_lshl_add_u64 v[82:83], v[80:81], 0, v[0:1]
	global_store_dwordx4 v[82:83], v[12:15], off sc0 sc1
	v_or_b32_e32 v0, s8, v59
	v_lshlrev_b32_e32 v0, 11, v0
	v_cvt_pk_bf16_f32 v12, v19, v17
	v_cvt_pk_bf16_f32 v13, v21, v23
	v_cvt_pk_bf16_f32 v14, v73, v75
	v_cvt_pk_bf16_f32 v15, v77, v79
	ds_read2_b32 v[18:19], v63 offset0:49 offset1:57
	ds_read2_b32 v[20:21], v63 offset0:16 offset1:24
	ds_read2_b32 v[22:23], v63 offset0:82 offset1:90
	ds_read2_b32 v[72:73], v63 offset0:115 offset1:123
	ds_read2_b32 v[74:75], v63 offset0:148 offset1:156
	ds_read2_b32 v[76:77], v63 offset0:181 offset1:189
	ds_read2_b32 v[78:79], v63 offset0:214 offset1:222
	ds_read2_b32 v[82:83], v63 offset0:247 offset1:255
	v_lshl_add_u64 v[16:17], v[80:81], 0, v[0:1]
	v_or_b32_e32 v0, s8, v60
	v_lshlrev_b32_e32 v0, 11, v0
	global_store_dwordx4 v[16:17], v[12:15], off sc0 sc1
	v_lshl_add_u64 v[16:17], v[80:81], 0, v[0:1]
	v_or_b32_e32 v0, s8, v61
	s_waitcnt lgkmcnt(6)
	v_cvt_pk_bf16_f32 v12, v20, v18
	s_waitcnt lgkmcnt(4)
	v_cvt_pk_bf16_f32 v13, v22, v72
	s_waitcnt lgkmcnt(2)
	v_cvt_pk_bf16_f32 v14, v74, v76
	s_waitcnt lgkmcnt(0)
	v_cvt_pk_bf16_f32 v15, v78, v82
	v_lshlrev_b32_e32 v0, 11, v0
	global_store_dwordx4 v[16:17], v[12:15], off sc0 sc1
	v_lshl_add_u64 v[16:17], v[80:81], 0, v[0:1]
	s_nop 0
	v_cvt_pk_bf16_f32 v12, v21, v19
	v_cvt_pk_bf16_f32 v13, v23, v73
	v_cvt_pk_bf16_f32 v14, v75, v77
	v_cvt_pk_bf16_f32 v15, v79, v83
	global_store_dwordx4 v[16:17], v[12:15], off sc0 sc1
	s_waitcnt lgkmcnt(0)

; #define LAS __attribute__((address_space(3)))
; __device__ __forceinline__ unsigned pk_bf16(float lo, float hi) { typedef __bf16 b2 __attribute__((ext_vector_type(2))); f32x2 v = {lo, hi}; b2 b = __builtin_convertvector(v, b2); return __builtin_bit_cast(unsigned, b); }
; __device__ __forceinline__ int wt_row_of_col(int n) {
;     if (n < 4096) return n;
;     if (n >= 9216) return 4096 + (n - 9216);
;     int a = n - 4096;
;     if (a < 3072) { const int e = a & 63; a = (a - e) + (e < 32 ? 2 * e : 2 * (e - 32) + 1); }
;     return 6144 + a;
; }
; template <bool MAP> __device__ __forceinline__ void p0_transpose_item(const float* W, int K, int N, u16* WT, LAS float* scr, int item, int lane) {
;     ...
;     for (int j = 0; j < 4; ++j) { const int n = (lane >> 3) + 8 * j; const LAS float* s = scr + (8 * c) * 33 + n;
;         u32x4 o; o.x = pk_bf16(s[0 * 33], s[1 * 33]); o.y = pk_bf16(s[2 * 33], s[3 * 33]); o.z = pk_bf16(s[4 * 33], s[5 * 33]); o.w = pk_bf16(s[6 * 33], s[7 * 33]);
;         const int r = MAP ? wt_row_of_col(n0 + n) : (n0 + n);
;         *(u32x4*)(WT + (size_t)r * K + k0 + 8 * c) = o; }
.LBB0_40:
	s_or_b64 exec, exec, s[12:13]
	s_ashr_i32 s11, s10, 31
	v_ashrrev_i32_e32 v23, 31, v22
	v_lshl_add_u64 v[12:13], s[10:11], 1, v[4:5]
	s_waitcnt lgkmcnt(3)
	v_cvt_pk_bf16_f32 v72, v14, v15
	v_lshlrev_b64 v[14:15], 11, v[22:23]
	s_waitcnt lgkmcnt(2)
	v_cvt_pk_bf16_f32 v73, v16, v17
	s_waitcnt lgkmcnt(1)
	v_cvt_pk_bf16_f32 v74, v18, v19
	s_waitcnt lgkmcnt(0)
	v_cvt_pk_bf16_f32 v75, v20, v21
	v_lshl_add_u64 v[22:23], v[12:13], 0, v[14:15]
	ds_read2_b32 v[14:15], v63 offset0:8 offset1:41
	ds_read2_b32 v[16:17], v63 offset0:74 offset1:107
	ds_read2_b32 v[18:19], v63 offset0:140 offset1:173
	ds_read2_b32 v[20:21], v63 offset0:206 offset1:239
	global_store_dwordx4 v[22:23], v[72:75], off sc0 sc1
	v_add_u32_e32 v23, 8, v0
	v_or_b32_e32 v22, s6, v59
	v_cmp_lt_i32_e32 vcc, s27, v23
	s_and_saveexec_b64 s[10:11], vcc
	s_cbranch_execz .LBB0_45
	s_cmpk_gt_u32 s8, 0x23ff
	s_mov_b64 s[12:13], -1
	s_cbranch_scc1 .LBB0_43
	v_and_b32_e32 v23, 47, v23
	v_lshlrev_b32_e32 v72, 1, v23
	v_add_u32_e32 v22, 0xfffff008, v0
	v_subrev_u32_e32 v73, 63, v72
	v_cmp_gt_u32_e32 vcc, 32, v23
	s_cmpk_lt_u32 s8, 0x1c00
	v_and_b32_e32 v71, 0xffffffc0, v22
	v_cndmask_b32_e32 v23, v73, v72, vcc
	v_add_u32_e32 v23, v23, v71
	s_cselect_b64 vcc, -1, 0
	v_cndmask_b32_e32 v22, v22, v23, vcc
	v_add_u32_e32 v22, 0x1800, v22
	s_mov_b64 s[12:13], 0

; #define LAS __attribute__((address_space(3)))
; __device__ __forceinline__ unsigned pk_bf16(float lo, float hi) { typedef __bf16 b2 __attribute__((ext_vector_type(2))); f32x2 v = {lo, hi}; b2 b = __builtin_convertvector(v, b2); return __builtin_bit_cast(unsigned, b); }
; __device__ __forceinline__ int wt_row_of_col(int n) {
;     if (n < 4096) return n;
;     if (n >= 9216) return 4096 + (n - 9216);
;     int a = n - 4096;
;     if (a < 3072) { const int e = a & 63; a = (a - e) + (e < 32 ? 2 * e : 2 * (e - 32) + 1); }
;     return 6144 + a;
; }
; template <bool MAP> __device__ __forceinline__ void p0_transpose_item(const float* W, int K, int N, u16* WT, LAS float* scr, int item, int lane) {
;     ...
;     for (int j = 0; j < 4; ++j) { const int n = (lane >> 3) + 8 * j; const LAS float* s = scr + (8 * c) * 33 + n;
;         u32x4 o; o.x = pk_bf16(s[0 * 33], s[1 * 33]); o.y = pk_bf16(s[2 * 33], s[3 * 33]); o.z = pk_bf16(s[4 * 33], s[5 * 33]); o.w = pk_bf16(s[6 * 33], s[7 * 33]);
;         const int r = MAP ? wt_row_of_col(n0 + n) : (n0 + n);
;         *(u32x4*)(WT + (size_t)r * K + k0 + 8 * c) = o; }
.LBB0_45:
	s_or_b64 exec, exec, s[10:11]
	v_ashrrev_i32_e32 v23, 31, v22
	s_waitcnt lgkmcnt(3)
	v_cvt_pk_bf16_f32 v72, v14, v15
	v_lshlrev_b64 v[14:15], 11, v[22:23]
	s_waitcnt lgkmcnt(2)
	v_cvt_pk_bf16_f32 v73, v16, v17
	s_waitcnt lgkmcnt(1)
	v_cvt_pk_bf16_f32 v74, v18, v19
	s_waitcnt lgkmcnt(0)
	v_cvt_pk_bf16_f32 v75, v20, v21
	v_lshl_add_u64 v[22:23], v[12:13], 0, v[14:15]
	ds_read2_b32 v[14:15], v63 offset0:16 offset1:49
	ds_read2_b32 v[16:17], v63 offset0:82 offset1:115
	ds_read2_b32 v[18:19], v63 offset0:148 offset1:181
	ds_read2_b32 v[20:21], v63 offset0:214 offset1:247
	global_store_dwordx4 v[22:23], v[72:75], off sc0 sc1
	v_add_u32_e32 v23, 16, v0
	v_or_b32_e32 v22, s6, v60
	v_cmp_lt_i32_e32 vcc, s27, v23
	s_and_saveexec_b64 s[10:11], vcc
	s_cbranch_execz .LBB0_50
	s_cmpk_gt_u32 s8, 0x23ff
	s_mov_b64 s[12:13], -1
	s_cbranch_scc1 .LBB0_48
	v_and_b32_e32 v23, 55, v23
	v_lshlrev_b32_e32 v72, 1, v23
	v_add_u32_e32 v22, 0xfffff010, v0
	v_subrev_u32_e32 v73, 63, v72
	v_cmp_gt_u32_e32 vcc, 32, v23
	s_cmpk_lt_u32 s8, 0x1c00
	v_and_b32_e32 v71, 0xffffffc0, v22
	v_cndmask_b32_e32 v23, v73, v72, vcc
	v_add_u32_e32 v23, v23, v71
	s_cselect_b64 vcc, -1, 0
	v_cndmask_b32_e32 v22, v22, v23, vcc
	v_add_u32_e32 v22, 0x1800, v22
	s_mov_b64 s[12:13], 0

; #define LAS __attribute__((address_space(3)))
; __device__ __forceinline__ unsigned pk_bf16(float lo, float hi) { typedef __bf16 b2 __attribute__((ext_vector_type(2))); f32x2 v = {lo, hi}; b2 b = __builtin_convertvector(v, b2); return __builtin_bit_cast(unsigned, b); }
; __device__ __forceinline__ int wt_row_of_col(int n) {
;     if (n < 4096) return n;
;     if (n >= 9216) return 4096 + (n - 9216);
;     int a = n - 4096;
;     if (a < 3072) { const int e = a & 63; a = (a - e) + (e < 32 ? 2 * e : 2 * (e - 32) + 1); }
;     return 6144 + a;
; }
; template <bool MAP> __device__ __forceinline__ void p0_transpose_item(const float* W, int K, int N, u16* WT, LAS float* scr, int item, int lane) {
;     ...
;     for (int j = 0; j < 4; ++j) { const int n = (lane >> 3) + 8 * j; const LAS float* s = scr + (8 * c) * 33 + n;
;         u32x4 o; o.x = pk_bf16(s[0 * 33], s[1 * 33]); o.y = pk_bf16(s[2 * 33], s[3 * 33]); o.z = pk_bf16(s[4 * 33], s[5 * 33]); o.w = pk_bf16(s[6 * 33], s[7 * 33]);
;         const int r = MAP ? wt_row_of_col(n0 + n) : (n0 + n);
;         *(u32x4*)(WT + (size_t)r * K + k0 + 8 * c) = o; }
.LBB0_50:
	s_or_b64 exec, exec, s[10:11]
	v_ashrrev_i32_e32 v23, 31, v22
	s_waitcnt lgkmcnt(3)
	v_cvt_pk_bf16_f32 v72, v14, v15
	v_lshlrev_b64 v[14:15], 11, v[22:23]
	s_waitcnt lgkmcnt(2)
	v_cvt_pk_bf16_f32 v73, v16, v17
	s_waitcnt lgkmcnt(1)
	v_cvt_pk_bf16_f32 v74, v18, v19
	s_waitcnt lgkmcnt(0)
	v_cvt_pk_bf16_f32 v75, v20, v21
	v_lshl_add_u64 v[22:23], v[12:13], 0, v[14:15]
	ds_read2_b32 v[14:15], v63 offset0:24 offset1:57
	ds_read2_b32 v[16:17], v63 offset0:90 offset1:123
	ds_read2_b32 v[18:19], v63 offset0:156 offset1:189
	ds_read2_b32 v[20:21], v63 offset0:222 offset1:255
	global_store_dwordx4 v[22:23], v[72:75], off sc0 sc1
	v_add_u32_e32 v23, 24, v0
	v_or_b32_e32 v22, s6, v61
	v_cmp_lt_i32_e32 vcc, s27, v23
	s_and_saveexec_b64 s[10:11], vcc
	s_cbranch_execz .LBB0_22
	s_cmpk_gt_u32 s8, 0x23ff
	s_mov_b64 s[12:13], -1
	s_cbranch_scc1 .LBB0_53
	v_and_b32_e32 v23, 63, v23
	v_lshlrev_b32_e32 v72, 1, v23
	v_add_u32_e32 v22, 0xfffff018, v0
	v_subrev_u32_e32 v73, 63, v72
	v_cmp_gt_u32_e32 vcc, 32, v23
	s_cmpk_lt_u32 s8, 0x1c00
	v_and_b32_e32 v71, 0xffffffc0, v22
	v_cndmask_b32_e32 v23, v73, v72, vcc
	v_add_u32_e32 v23, v23, v71
	s_cselect_b64 vcc, -1, 0
	v_cndmask_b32_e32 v22, v22, v23, vcc
	v_add_u32_e32 v22, 0x1800, v22
	s_mov_b64 s[12:13], 0

; __device__ __forceinline__ void p0_prologue(const Ptrs& P, LAS unsigned char* lds, int vcu, int G) {
;     ...
;     for (int m = gw; m < TT; m += 2 * NGW) {
;         const int m2 = (m + NGW < TT) ? m + NGW : m;
;         const f32x4* xr = (const f32x4*)(P.x + (size_t)m * DM) + lane; const f32x4* xr2 = (const f32x4*)(P.x + (size_t)m2 * DM) + lane; f32x4 v[4], v2[4]; float s = 0.f, s2 = 0.f;
; #pragma unroll
;         for (int j = 0; j < 4; ++j) { v[j] = xr[64 * j]; v2[j] = xr2[64 * j]; }
; #pragma unroll
;         for (int j = 0; j < 4; ++j) { s += (v[j].x * v[j].x + v[j].y * v[j].y) + (v[j].z * v[j].z + v[j].w * v[j].w); s2 += (v2[j].x * v2[j].x + v2[j].y * v2[j].y) + (v2[j].z * v2[j].z + v2[j].w * v2[j].w); }
;         const float rstd = rsqrtf(wave_sum(s) * (1.0f / DM) + NORM_EPS), rstd2 = rsqrtf(wave_sum(s2) * (1.0f / DM) + NORM_EPS);
.LBB0_57:
	s_add_i32 s8, s0, s17
	s_cmpk_lt_i32 s8, 0x4000
	s_cselect_b32 s10, s8, s0
	s_ashr_i32 s1, s0, 31
	s_lshl_b64 s[12:13], s[0:1], 12
	s_ashr_i32 s11, s10, 31
	v_lshl_add_u64 v[22:23], v[2:3], 0, s[12:13]
	s_lshl_b64 s[12:13], s[10:11], 12
	global_load_dwordx4 v[18:21], v[22:23], off nt
	global_load_dwordx4 v[26:29], v[22:23], off offset:1024 nt
	global_load_dwordx4 v[30:33], v[22:23], off offset:3072 nt
	global_load_dwordx4 v[34:37], v[22:23], off offset:2048 nt
	v_lshl_add_u64 v[22:23], v[2:3], 0, s[12:13]
	global_load_dwordx4 v[38:41], v[22:23], off nt
	global_load_dwordx4 v[42:45], v[22:23], off offset:1024 nt
	global_load_dwordx4 v[46:49], v[22:23], off offset:3072 nt
	global_load_dwordx4 v[50:53], v[22:23], off offset:2048 nt
	s_lshl_b64 s[0:1], s[0:1], 11
	v_lshl_add_u64 v[54:55], v[0:1], 0, s[0:1]
	s_lshl_b64 s[0:1], s[10:11], 11
	v_lshl_add_u64 v[56:57], v[0:1], 0, s[0:1]
	s_waitcnt vmcnt(7)
	v_pk_mul_f32 v[22:23], v[20:21], v[20:21]
	v_pk_mul_f32 v[58:59], v[18:19], v[18:19]
	s_waitcnt vmcnt(6)
	v_pk_mul_f32 v[60:61], v[28:29], v[28:29]
	v_pk_mul_f32 v[62:63], v[26:27], v[26:27]
	s_waitcnt vmcnt(4)
	v_mul_f32_e32 v64, v35, v35
	v_mul_f32_e32 v66, v37, v37
	v_pk_mov_b32 v[68:69], v[58:59], v[22:23] op_sel:[1,0]
	v_mov_b32_e32 v59, v23
	s_waitcnt vmcnt(3)
	v_pk_mul_f32 v[22:23], v[40:41], v[40:41]
	v_pk_mul_f32 v[70:71], v[38:39], v[38:39]
	v_pk_mov_b32 v[72:73], v[62:63], v[60:61] op_sel:[1,0]
	v_mov_b32_e32 v63, v61
	s_waitcnt vmcnt(2)
	v_pk_mul_f32 v[60:61], v[44:45], v[44:45]
	v_pk_mul_f32 v[74:75], v[42:43], v[42:43]
	v_mul_f32_e32 v77, v32, v32
	v_mul_f32_e32 v79, v33, v33
	v_pk_fma_f32 v[64:65], v[34:35], v[34:35], v[64:65] op_sel_hi:[1,1,0]
	v_pk_fma_f32 v[66:67], v[36:37], v[36:37], v[66:67] op_sel_hi:[1,1,0]
	v_pk_add_f32 v[58:59], v[68:69], v[58:59]
	v_pk_mov_b32 v[68:69], v[70:71], v[22:23] op_sel:[1,0]
	v_mov_b32_e32 v71, v23
	v_pk_add_f32 v[22:23], v[72:73], v[62:63]
	v_pk_mov_b32 v[62:63], v[74:75], v[60:61] op_sel:[1,0]
	v_mov_b32_e32 v75, v61
	s_waitcnt vmcnt(0)
	v_mul_f32_e32 v76, v51, v51
	v_mul_f32_e32 v78, v53, v53
	v_mov_b32_e32 v65, v77
	v_mov_b32_e32 v67, v79
	v_pk_add_f32 v[68:69], v[68:69], v[70:71]
	v_pk_add_f32 v[62:63], v[62:63], v[74:75]
	v_mul_f32_e32 v13, v30, v30
	v_mul_f32_e32 v25, v31, v31
	v_mul_f32_e32 v80, v46, v46
	v_mul_f32_e32 v81, v47, v47
	v_mul_f32_e32 v82, v48, v48
	v_mul_f32_e32 v83, v49, v49
	v_pk_fma_f32 v[60:61], v[50:51], v[50:51], v[76:77] op_sel_hi:[1,1,0]
	v_pk_fma_f32 v[72:73], v[52:53], v[52:53], v[78:79] op_sel_hi:[1,1,0]
	v_pk_add_f32 v[58:59], v[58:59], v[58:59] op_sel:[0,1] op_sel_hi:[1,0]
	v_pk_add_f32 v[22:23], v[22:23], v[22:23] op_sel:[0,1] op_sel_hi:[1,0]
	v_pk_add_f32 v[64:65], v[64:65], v[66:67]
	v_pk_add_f32 v[66:67], v[68:69], v[68:69] op_sel:[0,1] op_sel_hi:[1,0]
	v_pk_add_f32 v[62:63], v[62:63], v[62:63] op_sel:[0,1] op_sel_hi:[1,0]
	v_mov_b32_e32 v61, v82
	v_mov_b32_e32 v73, v83
	v_mov_b32_e32 v59, v13
	v_mov_b32_e32 v23, v25
	v_mov_b32_e32 v67, v80
	v_mov_b32_e32 v63, v81
	v_pk_add_f32 v[60:61], v[60:61], v[72:73]
	v_pk_add_f32 v[22:23], v[58:59], v[22:23]
	v_pk_add_f32 v[58:59], v[66:67], v[62:63]
	v_pk_add_f32 v[22:23], v[22:23], v[64:65]
	v_pk_add_f32 v[58:59], v[58:59], v[60:61]
	v_mov_b32_e32 v61, v22
	v_mov_b32_e32 v60, v58
	v_mov_b32_e32 v22, v59
	v_pk_add_f32 v[22:23], v[60:61], v[22:23]
	ds_bpermute_b32 v59, v7, v23
	ds_bpermute_b32 v58, v7, v22
	s_waitcnt lgkmcnt(0)
	v_pk_add_f32 v[22:23], v[22:23], v[58:59]
	ds_bpermute_b32 v59, v8, v23
	ds_bpermute_b32 v58, v8, v22
	s_waitcnt lgkmcnt(0)
	v_pk_add_f32 v[22:23], v[22:23], v[58:59]
	ds_bpermute_b32 v59, v9, v23
	ds_bpermute_b32 v58, v9, v22
	s_waitcnt lgkmcnt(0)
; __device__ __forceinline__ unsigned pk_bf16(float lo, float hi) { typedef __bf16 b2 __attribute__((ext_vector_type(2))); f32x2 v = {lo, hi}; b2 b = __builtin_convertvector(v, b2); return __builtin_bit_cast(unsigned, b); }
; __device__ __forceinline__ void p0_prologue(const Ptrs& P, LAS unsigned char* lds, int vcu, int G) {
;     ...
;         const float rstd = rsqrtf(wave_sum(s) * (1.0f / DM) + NORM_EPS), rstd2 = rsqrtf(wave_sum(s2) * (1.0f / DM) + NORM_EPS);
;         u32x2* o8 = (u32x2*)(H + (size_t)m * DM) + lane; u32x2* o82 = (u32x2*)(H + (size_t)m2 * DM) + lane;
; #pragma unroll
;         for (int j = 0; j < 4; ++j) { const f32x4 w4 = ((const f32x4*)P.norm_w)[lane + 64 * j];
;             o8[64 * j] = (u32x2){pk_bf16(v[j].x * rstd * w4.x, v[j].y * rstd * w4.y), pk_bf16(v[j].z * rstd * w4.z, v[j].w * rstd * w4.w)};
;             o82[64 * j] = (u32x2){pk_bf16(v2[j].x * rstd2 * w4.x, v2[j].y * rstd2 * w4.y), pk_bf16(v2[j].z * rstd2 * w4.z, v2[j].w * rstd2 * w4.w)}; }
	v_pk_add_f32 v[22:23], v[22:23], v[58:59]
	ds_bpermute_b32 v59, v10, v23
	ds_bpermute_b32 v58, v10, v22
	s_waitcnt lgkmcnt(0)
	v_pk_add_f32 v[22:23], v[22:23], v[58:59]
	ds_bpermute_b32 v59, v11, v23
	ds_bpermute_b32 v58, v11, v22
	s_waitcnt lgkmcnt(0)
	v_pk_add_f32 v[22:23], v[22:23], v[58:59]
	ds_bpermute_b32 v59, v12, v23
	ds_bpermute_b32 v58, v12, v22
	s_waitcnt lgkmcnt(0)
	v_pk_add_f32 v[22:23], v[22:23], v[58:59]
	s_nop 0
	v_pk_fma_f32 v[22:23], v[22:23], s[6:7], v[6:7] op_sel_hi:[1,0,0]
	s_nop 0
	v_mul_f32_e32 v13, 0x4b800000, v23
	v_cmp_gt_f32_e64 s[0:1], s7, v23
	v_mul_f32_e32 v25, 0x4b800000, v22
	v_cmp_gt_f32_e32 vcc, s7, v22
	v_cndmask_b32_e64 v13, v23, v13, s[0:1]
	v_rsq_f32_e32 v13, v13
	v_cndmask_b32_e32 v22, v22, v25, vcc
	v_rsq_f32_e32 v23, v22
	v_mul_f32_e32 v22, 0x45800000, v13
	v_cndmask_b32_e64 v22, v13, v22, s[0:1]
	v_mul_f32_e32 v25, 0x45800000, v23
	v_cndmask_b32_e32 v58, v23, v25, vcc
	v_pk_mul_f32 v[18:19], v[18:19], v[22:23] op_sel_hi:[1,0]
	v_pk_mul_f32 v[20:21], v[20:21], v[22:23] op_sel_hi:[1,0]
	v_pk_mul_f32 v[38:39], v[38:39], v[58:59] op_sel_hi:[1,0]
	v_pk_mul_f32 v[40:41], v[40:41], v[58:59] op_sel_hi:[1,0]
	v_pk_mul_f32 v[18:19], v[100:101], v[18:19]
	v_pk_mul_f32 v[20:21], v[102:103], v[20:21]
	v_pk_mul_f32 v[14:15], v[100:101], v[38:39]
	v_pk_mul_f32 v[16:17], v[102:103], v[40:41]
	v_cvt_pk_bf16_f32 v18, v18, v19
	v_cvt_pk_bf16_f32 v19, v20, v21
	v_cvt_pk_bf16_f32 v14, v14, v15
	v_cvt_pk_bf16_f32 v15, v16, v17
	global_store_dwordx2 v[54:55], v[18:19], off sc0 sc1
	global_store_dwordx2 v[56:57], v[14:15], off sc0 sc1
	v_pk_mul_f32 v[18:19], v[26:27], v[22:23] op_sel_hi:[1,0]
	v_pk_mul_f32 v[20:21], v[28:29], v[22:23] op_sel_hi:[1,0]
	v_pk_mul_f32 v[26:27], v[42:43], v[58:59] op_sel_hi:[1,0]
	v_pk_mul_f32 v[28:29], v[44:45], v[58:59] op_sel_hi:[1,0]
	s_add_i32 s0, s8, s17
	s_cmpk_gt_i32 s0, 0x3fff
	v_pk_mul_f32 v[18:19], v[104:105], v[18:19]
	v_pk_mul_f32 v[20:21], v[106:107], v[20:21]
	v_pk_mul_f32 v[14:15], v[104:105], v[26:27]
	v_pk_mul_f32 v[16:17], v[106:107], v[28:29]
	v_cvt_pk_bf16_f32 v18, v18, v19
	v_cvt_pk_bf16_f32 v19, v20, v21
	v_cvt_pk_bf16_f32 v14, v14, v15
	v_cvt_pk_bf16_f32 v15, v16, v17
	global_store_dwordx2 v[54:55], v[18:19], off offset:512 sc0 sc1
	global_store_dwordx2 v[56:57], v[14:15], off offset:512 sc0 sc1
	v_pk_mul_f32 v[18:19], v[34:35], v[22:23] op_sel_hi:[1,0]
	v_pk_mul_f32 v[20:21], v[36:37], v[22:23] op_sel_hi:[1,0]
	v_pk_mul_f32 v[26:27], v[50:51], v[58:59] op_sel_hi:[1,0]
	v_pk_mul_f32 v[28:29], v[52:53], v[58:59] op_sel_hi:[1,0]
	v_pk_mul_f32 v[18:19], v[18:19], v[108:109]
	v_pk_mul_f32 v[20:21], v[20:21], v[110:111]
	v_pk_mul_f32 v[14:15], v[108:109], v[26:27]
	v_pk_mul_f32 v[16:17], v[110:111], v[28:29]
	v_cvt_pk_bf16_f32 v18, v18, v19
	v_cvt_pk_bf16_f32 v19, v20, v21
	v_cvt_pk_bf16_f32 v14, v14, v15
	v_cvt_pk_bf16_f32 v15, v16, v17
	global_store_dwordx2 v[54:55], v[18:19], off offset:1024 sc0 sc1
	global_store_dwordx2 v[56:57], v[14:15], off offset:1024 sc0 sc1
	v_pk_mul_f32 v[18:19], v[30:31], v[22:23] op_sel_hi:[1,0]
	v_pk_mul_f32 v[20:21], v[32:33], v[22:23] op_sel_hi:[1,0]
	v_pk_mul_f32 v[22:23], v[46:47], v[58:59] op_sel_hi:[1,0]
	v_pk_mul_f32 v[26:27], v[48:49], v[58:59] op_sel_hi:[1,0]
	v_pk_mul_f32 v[18:19], v[18:19], v[112:113]
	v_pk_mul_f32 v[20:21], v[20:21], v[114:115]
	v_pk_mul_f32 v[14:15], v[22:23], v[112:113]
	v_pk_mul_f32 v[16:17], v[26:27], v[114:115]
	v_cvt_pk_bf16_f32 v18, v18, v19
	v_cvt_pk_bf16_f32 v19, v20, v21
	v_cvt_pk_bf16_f32 v14, v14, v15
	v_cvt_pk_bf16_f32 v15, v16, v17
	global_store_dwordx2 v[54:55], v[18:19], off offset:1536 sc0 sc1
	global_store_dwordx2 v[56:57], v[14:15], off offset:1536 sc0 sc1
	s_cbranch_scc0 .LBB0_57

; __device__ __forceinline__ void p0_prologue(const Ptrs& P, LAS unsigned char* lds, int vcu, int G) {
;     ...
;     for (int e = (vcu * 512 + tid); e < TT * 32; e += G * 512) {
;         const int row = e >> 5, j = e & 31;
;         const float inv = exp2f(-(float)j * (13.287712379549449f / 32.0f));
;         const float ang = (float)P.pos[row] * inv;
;         const double rev = (double)ang * 0.15915494309189535; const float fr = (float)(rev - __builtin_rint(rev));
;         cosT[e] = __builtin_amdgcn_cosf(fr); sinT[e] = __builtin_amdgcn_sinf(fr);
.LBB0_60:
	v_ashrrev_i32_e32 v6, 5, v0
	v_ashrrev_i32_e32 v7, 31, v6
	s_waitcnt lgkmcnt(0)
	v_lshl_add_u64 v[6:7], v[6:7], 2, s[58:59]
	global_load_dword v1, v[6:7], off nt
	v_add_co_u32_e32 v6, vcc, 0x200000, v2
	v_add_u32_e32 v0, s6, v0
	s_nop 0
	v_addc_co_u32_e32 v7, vcc, 0, v3, vcc
	v_cmp_lt_i32_e32 vcc, s7, v0
	s_or_b64 s[10:11], vcc, s[10:11]
	s_waitcnt vmcnt(0)
	v_cvt_f32_i32_e32 v1, v1
	v_mul_f32_e32 v1, v4, v1
	v_cvt_f64_f32_e32 v[8:9], v1
	v_mul_f64 v[10:11], v[8:9], s[12:13]
	v_rndne_f64_e32 v[10:11], v[10:11]
	v_fma_f64 v[8:9], v[8:9], s[12:13], -v[10:11]
	v_cvt_f32_f64_e32 v1, v[8:9]
	v_cos_f32_e32 v5, v1
	v_sin_f32_e32 v1, v1
	global_store_dword v[2:3], v5, off sc0 sc1
	global_store_dword v[6:7], v1, off sc0 sc1
	v_lshl_add_u64 v[2:3], v[2:3], 0, s[8:9]
	s_andn2_b64 exec, exec, s[10:11]
	s_cbranch_execnz .LBB0_60
